# in-proj epilogue: hand-written path for the tiles stored as projected (no rotary, no gelu), on top of the P1 epilogue and prologue changes
# baseline (speedup 1.0000x reference)
.LBB0_567:
	s_waitcnt vmcnt(0)
	s_cmp_eq_u32 s83, 1
	s_cbranch_scc1 .Lipfa_slow
	s_add_i32 s0, s83, -3
	s_cmp_lt_u32 s0, 2
	s_cbranch_scc1 .Lipfa_slow
	s_add_u32 s10, s28, s12
	s_addc_u32 s11, s29, s13
	v_lshlrev_b32_e32 v204, 11, v198
	v_lshl_add_u32 v204, v202, 1, v204
	v_fmamk_f32 v206, v200, 0x3a800000, v228
	v_rsq_f32_e32 v206, v206
	v_fmamk_f32 v208, v231, 0x3a800000, v228
	v_rsq_f32_e32 v208, v208
	v_fmamk_f32 v210, v239, 0x3a800000, v228
	v_rsq_f32_e32 v210, v210
	v_pk_fma_f32 v[156:157], v[156:157], v[206:207], v[44:45] op_sel_hi:[1,0,1]
	v_pk_fma_f32 v[158:159], v[158:159], v[206:207], v[46:47] op_sel_hi:[1,0,1]
	v_pk_fma_f32 v[152:153], v[152:153], v[206:207], v[40:41] op_sel_hi:[1,0,1]
	v_pk_fma_f32 v[154:155], v[154:155], v[206:207], v[42:43] op_sel_hi:[1,0,1]
	v_pk_fma_f32 v[148:149], v[148:149], v[206:207], v[36:37] op_sel_hi:[1,0,1]
	v_pk_fma_f32 v[150:151], v[150:151], v[206:207], v[38:39] op_sel_hi:[1,0,1]
	v_pk_fma_f32 v[144:145], v[144:145], v[206:207], v[32:33] op_sel_hi:[1,0,1]
	v_pk_fma_f32 v[146:147], v[146:147], v[206:207], v[34:35] op_sel_hi:[1,0,1]
	v_cvt_pk_bf16_f32 v214, v156, v157
	v_cvt_pk_bf16_f32 v215, v158, v159
	v_cvt_pk_bf16_f32 v216, v152, v153
	v_cvt_pk_bf16_f32 v217, v154, v155
	global_store_dwordx4 v204, v[214:217], s[10:11]
	v_cvt_pk_bf16_f32 v218, v148, v149
	v_cvt_pk_bf16_f32 v219, v150, v151
	v_cvt_pk_bf16_f32 v220, v144, v145
	v_cvt_pk_bf16_f32 v221, v146, v147
	global_store_dwordx4 v204, v[218:221], s[10:11] offset:256
	s_add_u32 s10, s10, 0x8000
	s_addc_u32 s11, s11, 0
	v_fmamk_f32 v212, v238, 0x3a800000, v228
	v_rsq_f32_e32 v212, v212
	v_pk_fma_f32 v[108:109], v[108:109], v[208:209], v[44:45] op_sel_hi:[1,0,1]
	v_pk_fma_f32 v[110:111], v[110:111], v[208:209], v[46:47] op_sel_hi:[1,0,1]
	v_pk_fma_f32 v[104:105], v[104:105], v[208:209], v[40:41] op_sel_hi:[1,0,1]
	v_pk_fma_f32 v[106:107], v[106:107], v[208:209], v[42:43] op_sel_hi:[1,0,1]
	v_pk_fma_f32 v[100:101], v[100:101], v[208:209], v[36:37] op_sel_hi:[1,0,1]
	v_pk_fma_f32 v[102:103], v[102:103], v[208:209], v[38:39] op_sel_hi:[1,0,1]
	v_pk_fma_f32 v[96:97], v[96:97], v[208:209], v[32:33] op_sel_hi:[1,0,1]
	v_pk_fma_f32 v[98:99], v[98:99], v[208:209], v[34:35] op_sel_hi:[1,0,1]
	v_cvt_pk_bf16_f32 v214, v108, v109
	v_cvt_pk_bf16_f32 v215, v110, v111
	v_cvt_pk_bf16_f32 v216, v104, v105
	v_cvt_pk_bf16_f32 v217, v106, v107
	global_store_dwordx4 v204, v[214:217], s[10:11]
	v_cvt_pk_bf16_f32 v218, v100, v101
	v_cvt_pk_bf16_f32 v219, v102, v103
	v_cvt_pk_bf16_f32 v220, v96, v97
	v_cvt_pk_bf16_f32 v221, v98, v99
	global_store_dwordx4 v204, v[218:221], s[10:11] offset:256
	s_add_u32 s10, s10, 0x8000
	s_addc_u32 s11, s11, 0
	v_fmamk_f32 v206, v237, 0x3a800000, v228
	v_rsq_f32_e32 v206, v206
	v_pk_fma_f32 v[172:173], v[172:173], v[210:211], v[44:45] op_sel_hi:[1,0,1]
	v_pk_fma_f32 v[174:175], v[174:175], v[210:211], v[46:47] op_sel_hi:[1,0,1]
	v_pk_fma_f32 v[168:169], v[168:169], v[210:211], v[40:41] op_sel_hi:[1,0,1]
	v_pk_fma_f32 v[170:171], v[170:171], v[210:211], v[42:43] op_sel_hi:[1,0,1]
	v_pk_fma_f32 v[164:165], v[164:165], v[210:211], v[36:37] op_sel_hi:[1,0,1]
	v_pk_fma_f32 v[166:167], v[166:167], v[210:211], v[38:39] op_sel_hi:[1,0,1]
	v_pk_fma_f32 v[160:161], v[160:161], v[210:211], v[32:33] op_sel_hi:[1,0,1]
	v_pk_fma_f32 v[162:163], v[162:163], v[210:211], v[34:35] op_sel_hi:[1,0,1]
	v_cvt_pk_bf16_f32 v214, v172, v173
	v_cvt_pk_bf16_f32 v215, v174, v175
	v_cvt_pk_bf16_f32 v216, v168, v169
	v_cvt_pk_bf16_f32 v217, v170, v171
	global_store_dwordx4 v204, v[214:217], s[10:11]
	v_cvt_pk_bf16_f32 v218, v164, v165
	v_cvt_pk_bf16_f32 v219, v166, v167
	v_cvt_pk_bf16_f32 v220, v160, v161
	v_cvt_pk_bf16_f32 v221, v162, v163
	global_store_dwordx4 v204, v[218:221], s[10:11] offset:256
	s_add_u32 s10, s10, 0x8000
	s_addc_u32 s11, s11, 0
	v_fmamk_f32 v208, v236, 0x3a800000, v228
	v_rsq_f32_e32 v208, v208
	v_pk_fma_f32 v[140:141], v[140:141], v[212:213], v[44:45] op_sel_hi:[1,0,1]
	v_pk_fma_f32 v[142:143], v[142:143], v[212:213], v[46:47] op_sel_hi:[1,0,1]
	v_pk_fma_f32 v[136:137], v[136:137], v[212:213], v[40:41] op_sel_hi:[1,0,1]
	v_pk_fma_f32 v[138:139], v[138:139], v[212:213], v[42:43] op_sel_hi:[1,0,1]
	v_pk_fma_f32 v[132:133], v[132:133], v[212:213], v[36:37] op_sel_hi:[1,0,1]
	v_pk_fma_f32 v[134:135], v[134:135], v[212:213], v[38:39] op_sel_hi:[1,0,1]
	v_pk_fma_f32 v[128:129], v[128:129], v[212:213], v[32:33] op_sel_hi:[1,0,1]
	v_pk_fma_f32 v[130:131], v[130:131], v[212:213], v[34:35] op_sel_hi:[1,0,1]
	v_cvt_pk_bf16_f32 v214, v140, v141
	v_cvt_pk_bf16_f32 v215, v142, v143
	v_cvt_pk_bf16_f32 v216, v136, v137
	v_cvt_pk_bf16_f32 v217, v138, v139
	global_store_dwordx4 v204, v[214:217], s[10:11]
	v_cvt_pk_bf16_f32 v218, v132, v133
	v_cvt_pk_bf16_f32 v219, v134, v135
	v_cvt_pk_bf16_f32 v220, v128, v129
	v_cvt_pk_bf16_f32 v221, v130, v131
	global_store_dwordx4 v204, v[218:221], s[10:11] offset:256
	s_add_u32 s10, s10, 0x28000
	s_addc_u32 s11, s11, 0
	v_fmamk_f32 v210, v234, 0x3a800000, v228
	v_rsq_f32_e32 v210, v210
	v_pk_fma_f32 v[92:93], v[92:93], v[206:207], v[44:45] op_sel_hi:[1,0,1]
	v_pk_fma_f32 v[94:95], v[94:95], v[206:207], v[46:47] op_sel_hi:[1,0,1]
	v_pk_fma_f32 v[88:89], v[88:89], v[206:207], v[40:41] op_sel_hi:[1,0,1]
	v_pk_fma_f32 v[90:91], v[90:91], v[206:207], v[42:43] op_sel_hi:[1,0,1]
	v_pk_fma_f32 v[72:73], v[72:73], v[206:207], v[36:37] op_sel_hi:[1,0,1]
	v_pk_fma_f32 v[74:75], v[74:75], v[206:207], v[38:39] op_sel_hi:[1,0,1]
	v_pk_fma_f32 v[68:69], v[68:69], v[206:207], v[32:33] op_sel_hi:[1,0,1]
	v_pk_fma_f32 v[70:71], v[70:71], v[206:207], v[34:35] op_sel_hi:[1,0,1]
	v_cvt_pk_bf16_f32 v214, v92, v93
	v_cvt_pk_bf16_f32 v215, v94, v95
	v_cvt_pk_bf16_f32 v216, v88, v89
	v_cvt_pk_bf16_f32 v217, v90, v91
	global_store_dwordx4 v204, v[214:217], s[10:11]
	v_cvt_pk_bf16_f32 v218, v72, v73
	v_cvt_pk_bf16_f32 v219, v74, v75
	v_cvt_pk_bf16_f32 v220, v68, v69
	v_cvt_pk_bf16_f32 v221, v70, v71
	global_store_dwordx4 v204, v[218:221], s[10:11] offset:256
	s_add_u32 s10, s10, 0x8000
	s_addc_u32 s11, s11, 0
	v_fmamk_f32 v212, v233, 0x3a800000, v228
	v_rsq_f32_e32 v212, v212
	v_pk_fma_f32 v[60:61], v[60:61], v[208:209], v[44:45] op_sel_hi:[1,0,1]
	v_pk_fma_f32 v[62:63], v[62:63], v[208:209], v[46:47] op_sel_hi:[1,0,1]
	v_pk_fma_f32 v[56:57], v[56:57], v[208:209], v[40:41] op_sel_hi:[1,0,1]
	v_pk_fma_f32 v[58:59], v[58:59], v[208:209], v[42:43] op_sel_hi:[1,0,1]
	v_pk_fma_f32 v[52:53], v[52:53], v[208:209], v[36:37] op_sel_hi:[1,0,1]
	v_pk_fma_f32 v[54:55], v[54:55], v[208:209], v[38:39] op_sel_hi:[1,0,1]
	v_pk_fma_f32 v[48:49], v[48:49], v[208:209], v[32:33] op_sel_hi:[1,0,1]
	v_pk_fma_f32 v[50:51], v[50:51], v[208:209], v[34:35] op_sel_hi:[1,0,1]
	v_cvt_pk_bf16_f32 v214, v60, v61
	v_cvt_pk_bf16_f32 v215, v62, v63
	v_cvt_pk_bf16_f32 v216, v56, v57
	v_cvt_pk_bf16_f32 v217, v58, v59
	global_store_dwordx4 v204, v[214:217], s[10:11]
	v_cvt_pk_bf16_f32 v218, v52, v53
	v_cvt_pk_bf16_f32 v219, v54, v55
	v_cvt_pk_bf16_f32 v220, v48, v49
	v_cvt_pk_bf16_f32 v221, v50, v51
	global_store_dwordx4 v204, v[218:221], s[10:11] offset:256
	s_add_u32 s10, s10, 0x8000
	s_addc_u32 s11, s11, 0
	v_pk_fma_f32 v[28:29], v[28:29], v[210:211], v[44:45] op_sel_hi:[1,0,1]
	v_pk_fma_f32 v[30:31], v[30:31], v[210:211], v[46:47] op_sel_hi:[1,0,1]
	v_pk_fma_f32 v[24:25], v[24:25], v[210:211], v[40:41] op_sel_hi:[1,0,1]
	v_pk_fma_f32 v[26:27], v[26:27], v[210:211], v[42:43] op_sel_hi:[1,0,1]
	v_pk_fma_f32 v[20:21], v[20:21], v[210:211], v[36:37] op_sel_hi:[1,0,1]
	v_pk_fma_f32 v[22:23], v[22:23], v[210:211], v[38:39] op_sel_hi:[1,0,1]
	v_pk_fma_f32 v[16:17], v[16:17], v[210:211], v[32:33] op_sel_hi:[1,0,1]
	v_pk_fma_f32 v[18:19], v[18:19], v[210:211], v[34:35] op_sel_hi:[1,0,1]
	v_cvt_pk_bf16_f32 v214, v28, v29
	v_cvt_pk_bf16_f32 v215, v30, v31
	v_cvt_pk_bf16_f32 v216, v24, v25
	v_cvt_pk_bf16_f32 v217, v26, v27
	global_store_dwordx4 v204, v[214:217], s[10:11]
	v_cvt_pk_bf16_f32 v218, v20, v21
	v_cvt_pk_bf16_f32 v219, v22, v23
	v_cvt_pk_bf16_f32 v220, v16, v17
	v_cvt_pk_bf16_f32 v221, v18, v19
	global_store_dwordx4 v204, v[218:221], s[10:11] offset:256
	s_add_u32 s10, s10, 0x8000
	s_addc_u32 s11, s11, 0
	v_pk_fma_f32 v[12:13], v[12:13], v[212:213], v[44:45] op_sel_hi:[1,0,1]
	v_pk_fma_f32 v[14:15], v[14:15], v[212:213], v[46:47] op_sel_hi:[1,0,1]
	v_pk_fma_f32 v[8:9], v[8:9], v[212:213], v[40:41] op_sel_hi:[1,0,1]
	v_pk_fma_f32 v[10:11], v[10:11], v[212:213], v[42:43] op_sel_hi:[1,0,1]
	v_pk_fma_f32 v[4:5], v[4:5], v[212:213], v[36:37] op_sel_hi:[1,0,1]
	v_pk_fma_f32 v[6:7], v[6:7], v[212:213], v[38:39] op_sel_hi:[1,0,1]
	v_pk_fma_f32 v[0:1], v[0:1], v[212:213], v[32:33] op_sel_hi:[1,0,1]
	v_pk_fma_f32 v[2:3], v[2:3], v[212:213], v[34:35] op_sel_hi:[1,0,1]
	v_cvt_pk_bf16_f32 v214, v12, v13
	v_cvt_pk_bf16_f32 v215, v14, v15
	v_cvt_pk_bf16_f32 v216, v8, v9
	v_cvt_pk_bf16_f32 v217, v10, v11
	global_store_dwordx4 v204, v[214:217], s[10:11]
	v_cvt_pk_bf16_f32 v218, v4, v5
	v_cvt_pk_bf16_f32 v219, v6, v7
	v_cvt_pk_bf16_f32 v220, v0, v1
	v_cvt_pk_bf16_f32 v221, v2, v3
	global_store_dwordx4 v204, v[218:221], s[10:11] offset:256
	s_andn2_b64 vcc, exec, s[6:7]
	s_mov_b64 s[6:7], -1
	s_cbranch_vccnz .LBB0_521
	s_andn2_b64 vcc, exec, s[60:61]
	s_cbranch_vccnz .LBB0_520
	s_barrier
	s_branch .LBB0_520
.Lipfa_slow:
	v_fmamk_f32 v184, v200, 0x3a800000, v228
	v_rsq_f32_e32 v184, v184
	s_cmp_eq_u32 s83, 4
	s_cselect_b64 s[10:11], -1, 0
	s_cmp_eq_u32 s83, 1
	s_cselect_b64 s[8:9], -1, 0
	v_pk_fma_f32 v[158:159], v[158:159], v[184:185], v[46:47] op_sel_hi:[1,0,1]
	v_pk_fma_f32 v[156:157], v[156:157], v[184:185], v[44:45] op_sel_hi:[1,0,1]
	v_pk_fma_f32 v[154:155], v[154:155], v[184:185], v[42:43] op_sel_hi:[1,0,1]
	v_pk_fma_f32 v[152:153], v[152:153], v[184:185], v[40:41] op_sel_hi:[1,0,1]
	v_pk_fma_f32 v[150:151], v[150:151], v[184:185], v[38:39] op_sel_hi:[1,0,1]
	v_pk_fma_f32 v[148:149], v[148:149], v[184:185], v[36:37] op_sel_hi:[1,0,1]
	v_pk_fma_f32 v[146:147], v[146:147], v[184:185], v[34:35] op_sel_hi:[1,0,1]
	v_pk_fma_f32 v[144:145], v[144:145], v[184:185], v[32:33] op_sel_hi:[1,0,1]
	v_cndmask_b32_e64 v184, 0, 1, s[8:9]
	s_mov_b64 s[94:95], -1
	s_and_b64 vcc, exec, s[92:93]
	v_cmp_ne_u32_e64 s[8:9], 1, v184
	s_cbranch_vccz .LBB0_573
	s_and_b64 vcc, exec, s[8:9]
	v_mov_b32_e32 v209, v159
	v_mov_b32_e32 v208, v158
	v_mov_b32_e32 v207, v157
	v_mov_b32_e32 v206, v156
	v_mov_b32_e32 v213, v155
	v_mov_b32_e32 v212, v154
	v_mov_b32_e32 v211, v153
	v_mov_b32_e32 v210, v152
	v_mov_b32_e32 v217, v151
	v_mov_b32_e32 v216, v150
	v_mov_b32_e32 v215, v149
	v_mov_b32_e32 v214, v148
	v_mov_b32_e32 v221, v147
	v_mov_b32_e32 v220, v146
	v_mov_b32_e32 v219, v145
	v_mov_b32_e32 v218, v144
	s_cbranch_vccnz .LBB0_572
	v_and_b32_e32 v201, 0x7fffffff, v157
	v_and_b32_e32 v200, 0x7fffffff, v156
	v_pk_fma_f32 v[200:201], v[200:201], s[68:69], 1.0 op_sel_hi:[1,0,0]
	v_pk_mul_f32 v[210:211], v[156:157], v[156:157]
	v_rcp_f32_e32 v206, v200
	v_rcp_f32_e32 v207, v201
	v_mov_b64_e32 v[200:201], s[72:73]
	v_pk_mul_f32 v[210:211], v[210:211], s[80:81] op_sel_hi:[1,0]
	v_cmp_gt_f32_e32 vcc, 0, v156
	v_pk_fma_f32 v[208:209], v[206:207], s[70:71], v[200:201] op_sel_hi:[1,0,0]
	v_exp_f32_e32 v210, v210
	v_pk_fma_f32 v[208:209], v[206:207], v[208:209], s[74:75] op_sel_hi:[1,1,0]
	v_exp_f32_e32 v211, v211
	v_pk_fma_f32 v[208:209], v[206:207], v[208:209], s[76:77] op_sel_hi:[1,1,0]
	v_pk_mul_f32 v[214:215], v[152:153], v[152:153]
	v_pk_fma_f32 v[208:209], v[206:207], v[208:209], s[78:79] op_sel_hi:[1,1,0]
	v_pk_mul_f32 v[214:215], v[214:215], s[80:81] op_sel_hi:[1,0]
	v_pk_mul_f32 v[206:207], v[206:207], v[208:209]
	v_pk_mul_f32 v[208:209], v[158:159], v[158:159]
	v_pk_mul_f32 v[206:207], v[210:211], v[206:207]
	v_pk_mul_f32 v[208:209], v[208:209], s[80:81] op_sel_hi:[1,0]
	v_pk_mul_f32 v[210:211], v[156:157], v[206:207]
	v_pk_fma_f32 v[206:207], v[156:157], v[206:207], v[156:157] neg_lo:[1,0,0] neg_hi:[1,0,0]
	v_exp_f32_e32 v208, v208
	v_cndmask_b32_e32 v206, v206, v210, vcc
	v_cmp_gt_f32_e32 vcc, 0, v157
	v_and_b32_e32 v210, 0x7fffffff, v158
	v_exp_f32_e32 v209, v209
	v_cndmask_b32_e32 v207, v207, v211, vcc
	v_and_b32_e32 v211, 0x7fffffff, v159
	v_pk_fma_f32 v[210:211], v[210:211], s[68:69], 1.0 op_sel_hi:[1,0,0]
	v_cmp_gt_f32_e32 vcc, 0, v158
	v_rcp_f32_e32 v210, v210
	v_rcp_f32_e32 v211, v211
	v_exp_f32_e32 v214, v214
	v_exp_f32_e32 v215, v215
	v_pk_mul_f32 v[218:219], v[148:149], v[148:149]
	v_pk_fma_f32 v[212:213], v[210:211], s[70:71], v[200:201] op_sel_hi:[1,0,0]
	v_pk_mul_f32 v[218:219], v[218:219], s[80:81] op_sel_hi:[1,0]
	v_pk_fma_f32 v[212:213], v[210:211], v[212:213], s[74:75] op_sel_hi:[1,1,0]
	v_exp_f32_e32 v218, v218
	v_pk_fma_f32 v[212:213], v[210:211], v[212:213], s[76:77] op_sel_hi:[1,1,0]
	v_exp_f32_e32 v219, v219
	v_pk_fma_f32 v[212:213], v[210:211], v[212:213], s[78:79] op_sel_hi:[1,1,0]
	v_pk_mul_f32 v[240:241], v[144:145], v[144:145]
	v_pk_mul_f32 v[210:211], v[210:211], v[212:213]
	v_pk_mul_f32 v[240:241], v[240:241], s[80:81] op_sel_hi:[1,0]
	v_pk_mul_f32 v[208:209], v[208:209], v[210:211]
	v_exp_f32_e32 v240, v240
	v_pk_mul_f32 v[210:211], v[158:159], v[208:209]
	v_pk_fma_f32 v[208:209], v[158:159], v[208:209], v[158:159] neg_lo:[1,0,0] neg_hi:[1,0,0]
	v_exp_f32_e32 v241, v241
	v_cndmask_b32_e32 v208, v208, v210, vcc
	v_cmp_gt_f32_e32 vcc, 0, v159
	v_and_b32_e32 v210, 0x7fffffff, v152
	v_add_f32_e32 v184, 0, v206
	v_cndmask_b32_e32 v209, v209, v211, vcc
	v_and_b32_e32 v211, 0x7fffffff, v153
	v_pk_fma_f32 v[210:211], v[210:211], s[68:69], 1.0 op_sel_hi:[1,0,0]
	v_cmp_gt_f32_e32 vcc, 0, v152
	v_rcp_f32_e32 v210, v210
	v_rcp_f32_e32 v211, v211
	v_add_f32_e32 v184, v207, v184
	v_add_f32_e32 v184, v208, v184
	v_add_f32_e32 v184, v209, v184
	v_pk_fma_f32 v[212:213], v[210:211], s[70:71], v[200:201] op_sel_hi:[1,0,0]
	v_and_b32_e32 v203, 64, v229
	v_pk_fma_f32 v[212:213], v[210:211], v[212:213], s[74:75] op_sel_hi:[1,1,0]
	v_add_u32_e32 v203, 64, v203
	v_pk_fma_f32 v[212:213], v[210:211], v[212:213], s[76:77] op_sel_hi:[1,1,0]
	s_nop 0
	v_pk_fma_f32 v[212:213], v[210:211], v[212:213], s[78:79] op_sel_hi:[1,1,0]
	s_nop 0
	v_pk_mul_f32 v[210:211], v[210:211], v[212:213]
	v_pk_mul_f32 v[212:213], v[154:155], v[154:155]
	v_pk_mul_f32 v[210:211], v[214:215], v[210:211]
	v_pk_mul_f32 v[212:213], v[212:213], s[80:81] op_sel_hi:[1,0]
	v_pk_mul_f32 v[214:215], v[152:153], v[210:211]
	v_pk_fma_f32 v[210:211], v[152:153], v[210:211], v[152:153] neg_lo:[1,0,0] neg_hi:[1,0,0]
	v_exp_f32_e32 v212, v212
	v_cndmask_b32_e32 v210, v210, v214, vcc
	v_cmp_gt_f32_e32 vcc, 0, v153
	v_and_b32_e32 v214, 0x7fffffff, v154
	v_exp_f32_e32 v213, v213
	v_cndmask_b32_e32 v211, v211, v215, vcc
	v_and_b32_e32 v215, 0x7fffffff, v155
	v_pk_fma_f32 v[214:215], v[214:215], s[68:69], 1.0 op_sel_hi:[1,0,0]
	v_cmp_gt_f32_e32 vcc, 0, v154
	v_rcp_f32_e32 v214, v214
	v_rcp_f32_e32 v215, v215
	v_add_f32_e32 v184, v210, v184
	v_add_f32_e32 v184, v211, v184
	v_pk_fma_f32 v[216:217], v[214:215], s[70:71], v[200:201] op_sel_hi:[1,0,0]
	s_nop 0
	v_pk_fma_f32 v[216:217], v[214:215], v[216:217], s[74:75] op_sel_hi:[1,1,0]
	s_nop 0
	v_pk_fma_f32 v[216:217], v[214:215], v[216:217], s[76:77] op_sel_hi:[1,1,0]
	s_nop 0
	v_pk_fma_f32 v[216:217], v[214:215], v[216:217], s[78:79] op_sel_hi:[1,1,0]
	s_nop 0
	v_pk_mul_f32 v[214:215], v[214:215], v[216:217]
	s_nop 0
	v_pk_mul_f32 v[212:213], v[212:213], v[214:215]
	s_nop 0
	v_pk_mul_f32 v[214:215], v[154:155], v[212:213]
	v_pk_fma_f32 v[212:213], v[154:155], v[212:213], v[154:155] neg_lo:[1,0,0] neg_hi:[1,0,0]
	s_nop 0
	v_cndmask_b32_e32 v212, v212, v214, vcc
	v_cmp_gt_f32_e32 vcc, 0, v155
	v_and_b32_e32 v214, 0x7fffffff, v148
	v_add_f32_e32 v184, v212, v184
	v_cndmask_b32_e32 v213, v213, v215, vcc
	v_and_b32_e32 v215, 0x7fffffff, v149
	v_pk_fma_f32 v[214:215], v[214:215], s[68:69], 1.0 op_sel_hi:[1,0,0]
	v_cmp_gt_f32_e32 vcc, 0, v148
	v_rcp_f32_e32 v214, v214
	v_rcp_f32_e32 v215, v215
	v_add_f32_e32 v184, v213, v184
	v_pk_fma_f32 v[216:217], v[214:215], s[70:71], v[200:201] op_sel_hi:[1,0,0]
	s_nop 0
	v_pk_fma_f32 v[216:217], v[214:215], v[216:217], s[74:75] op_sel_hi:[1,1,0]
	s_nop 0
	v_pk_fma_f32 v[216:217], v[214:215], v[216:217], s[76:77] op_sel_hi:[1,1,0]
	s_nop 0
	v_pk_fma_f32 v[216:217], v[214:215], v[216:217], s[78:79] op_sel_hi:[1,1,0]
	s_nop 0
	v_pk_mul_f32 v[214:215], v[214:215], v[216:217]
	v_pk_mul_f32 v[216:217], v[150:151], v[150:151]
	v_pk_mul_f32 v[214:215], v[218:219], v[214:215]
	v_pk_mul_f32 v[216:217], v[216:217], s[80:81] op_sel_hi:[1,0]
	v_pk_mul_f32 v[218:219], v[148:149], v[214:215]
	v_pk_fma_f32 v[214:215], v[148:149], v[214:215], v[148:149] neg_lo:[1,0,0] neg_hi:[1,0,0]
	v_exp_f32_e32 v216, v216
	v_cndmask_b32_e32 v214, v214, v218, vcc
	v_cmp_gt_f32_e32 vcc, 0, v149
	v_and_b32_e32 v218, 0x7fffffff, v150
	v_exp_f32_e32 v217, v217
	v_cndmask_b32_e32 v215, v215, v219, vcc
	v_and_b32_e32 v219, 0x7fffffff, v151
	v_pk_fma_f32 v[218:219], v[218:219], s[68:69], 1.0 op_sel_hi:[1,0,0]
	v_cmp_gt_f32_e32 vcc, 0, v150
	v_rcp_f32_e32 v218, v218
	v_rcp_f32_e32 v219, v219
	v_add_f32_e32 v184, v214, v184
	v_add_f32_e32 v184, v215, v184
	v_pk_fma_f32 v[220:221], v[218:219], s[70:71], v[200:201] op_sel_hi:[1,0,0]
	s_nop 0
	v_pk_fma_f32 v[220:221], v[218:219], v[220:221], s[74:75] op_sel_hi:[1,1,0]
	s_nop 0
	v_pk_fma_f32 v[220:221], v[218:219], v[220:221], s[76:77] op_sel_hi:[1,1,0]
	s_nop 0
	v_pk_fma_f32 v[220:221], v[218:219], v[220:221], s[78:79] op_sel_hi:[1,1,0]
	s_nop 0
	v_pk_mul_f32 v[218:219], v[218:219], v[220:221]
	s_nop 0
	v_pk_mul_f32 v[216:217], v[216:217], v[218:219]
	s_nop 0
	v_pk_mul_f32 v[218:219], v[150:151], v[216:217]
	v_pk_fma_f32 v[216:217], v[150:151], v[216:217], v[150:151] neg_lo:[1,0,0] neg_hi:[1,0,0]
	s_nop 0
	v_cndmask_b32_e32 v216, v216, v218, vcc
	v_cmp_gt_f32_e32 vcc, 0, v151
	v_and_b32_e32 v218, 0x7fffffff, v144
	v_add_f32_e32 v184, v216, v184
	v_cndmask_b32_e32 v217, v217, v219, vcc
	v_and_b32_e32 v219, 0x7fffffff, v145
	v_pk_fma_f32 v[218:219], v[218:219], s[68:69], 1.0 op_sel_hi:[1,0,0]
	v_cmp_gt_f32_e32 vcc, 0, v144
	v_rcp_f32_e32 v218, v218
	v_rcp_f32_e32 v219, v219
	v_add_f32_e32 v184, v217, v184
	v_pk_fma_f32 v[220:221], v[218:219], s[70:71], v[200:201] op_sel_hi:[1,0,0]
	s_nop 0
	v_pk_fma_f32 v[220:221], v[218:219], v[220:221], s[74:75] op_sel_hi:[1,1,0]
	s_nop 0
	v_pk_fma_f32 v[220:221], v[218:219], v[220:221], s[76:77] op_sel_hi:[1,1,0]
	s_nop 0
	v_pk_fma_f32 v[220:221], v[218:219], v[220:221], s[78:79] op_sel_hi:[1,1,0]
	s_nop 0
	v_pk_mul_f32 v[218:219], v[218:219], v[220:221]
	v_pk_mul_f32 v[220:221], v[146:147], v[146:147]
	v_pk_mul_f32 v[218:219], v[240:241], v[218:219]
	v_pk_mul_f32 v[220:221], v[220:221], s[80:81] op_sel_hi:[1,0]
	v_pk_mul_f32 v[240:241], v[144:145], v[218:219]
	v_pk_fma_f32 v[218:219], v[144:145], v[218:219], v[144:145] neg_lo:[1,0,0] neg_hi:[1,0,0]
	v_exp_f32_e32 v220, v220
	v_cndmask_b32_e32 v218, v218, v240, vcc
	v_cmp_gt_f32_e32 vcc, 0, v145
	v_and_b32_e32 v240, 0x7fffffff, v146
	v_exp_f32_e32 v221, v221
	v_cndmask_b32_e32 v219, v219, v241, vcc
	v_and_b32_e32 v241, 0x7fffffff, v147
	v_pk_fma_f32 v[240:241], v[240:241], s[68:69], 1.0 op_sel_hi:[1,0,0]
	v_cmp_gt_f32_e32 vcc, 0, v146
	v_rcp_f32_e32 v240, v240
	v_rcp_f32_e32 v241, v241
	v_add_f32_e32 v184, v218, v184
	v_add_f32_e32 v184, v219, v184
	v_pk_fma_f32 v[200:201], v[240:241], s[70:71], v[200:201] op_sel_hi:[1,0,0]
	s_nop 0
	v_pk_fma_f32 v[200:201], v[240:241], v[200:201], s[74:75] op_sel_hi:[1,1,0]
	s_nop 0
	v_pk_fma_f32 v[200:201], v[240:241], v[200:201], s[76:77] op_sel_hi:[1,1,0]
	s_nop 0
	v_pk_fma_f32 v[200:201], v[240:241], v[200:201], s[78:79] op_sel_hi:[1,1,0]
	s_nop 0
	v_pk_mul_f32 v[200:201], v[240:241], v[200:201]
	s_nop 0
	v_pk_mul_f32 v[200:201], v[220:221], v[200:201]
	s_nop 0
	v_pk_mul_f32 v[220:221], v[146:147], v[200:201]
	v_pk_fma_f32 v[200:201], v[146:147], v[200:201], v[146:147] neg_lo:[1,0,0] neg_hi:[1,0,0]
	s_nop 0
	v_cndmask_b32_e32 v220, v200, v220, vcc
	v_cmp_gt_f32_e32 vcc, 0, v147
	v_xor_b32_e32 v200, 16, v229
	v_add_f32_e32 v184, v220, v184
	v_cndmask_b32_e32 v221, v201, v221, vcc
	v_mul_f32_e32 v201, v207, v207
	v_fmac_f32_e32 v201, v206, v206
	v_fmac_f32_e32 v201, v208, v208
	v_fmac_f32_e32 v201, v209, v209
	v_fmac_f32_e32 v201, v210, v210
	v_fmac_f32_e32 v201, v211, v211
	v_fmac_f32_e32 v201, v212, v212
	v_fmac_f32_e32 v201, v213, v213
	v_fmac_f32_e32 v201, v214, v214
	v_fmac_f32_e32 v201, v215, v215
	v_fmac_f32_e32 v201, v216, v216
	v_cmp_lt_i32_e32 vcc, v200, v203
	v_fmac_f32_e32 v201, v217, v217
	v_fmac_f32_e32 v201, v218, v218
	v_cndmask_b32_e32 v200, v229, v200, vcc
	v_add_f32_e32 v184, v221, v184
	v_lshlrev_b32_e32 v205, 2, v200
	v_fmac_f32_e32 v201, v219, v219
	ds_bpermute_b32 v200, v205, v184
	v_fmac_f32_e32 v201, v220, v220
	v_fmac_f32_e32 v201, v221, v221
	ds_bpermute_b32 v205, v205, v201
	s_waitcnt lgkmcnt(1)
	v_add_f32_e32 v184, v184, v200
	v_xor_b32_e32 v200, 32, v229
	v_cmp_lt_i32_e32 vcc, v200, v203
	s_waitcnt lgkmcnt(0)
	v_add_f32_e32 v201, v201, v205
	v_cndmask_b32_e32 v200, v229, v200, vcc
	v_lshlrev_b32_e32 v203, 2, v200
	ds_bpermute_b32 v200, v203, v184
	ds_bpermute_b32 v203, v203, v201
	s_and_saveexec_b64 s[94:95], s[4:5]
	s_cbranch_execz .LBB0_571
	v_lshlrev_b64 v[240:241], 2, v[198:199]
	v_lshl_add_u64 v[242:243], s[14:15], 0, v[240:241]
	v_lshl_add_u64 v[240:241], s[52:53], 0, v[240:241]
	s_waitcnt lgkmcnt(1)
	v_add_f32_e32 v184, v184, v200
	s_waitcnt lgkmcnt(0)
	v_add_f32_e32 v200, v201, v203
	global_atomic_add_f32 v[240:241], v184, off
	global_atomic_add_f32 v[242:243], v200, off

.LBB0_826:
	s_waitcnt vmcnt(0)
	s_cmp_eq_u32 s18, 1
	s_cbranch_scc1 .Lipfb_slow
	s_add_i32 s8, s18, -3
	s_cmp_lt_u32 s8, 2
	s_cbranch_scc1 .Lipfb_slow
	s_add_u32 s0, s28, s10
	s_addc_u32 s1, s29, s11
	v_lshlrev_b32_e32 v204, 11, v198
	v_lshl_add_u32 v204, v202, 1, v204
	v_fmamk_f32 v206, v200, 0x3a800000, v228
	v_rsq_f32_e32 v206, v206
	v_fmamk_f32 v208, v231, 0x3a800000, v228
	v_rsq_f32_e32 v208, v208
	v_fmamk_f32 v210, v239, 0x3a800000, v228
	v_rsq_f32_e32 v210, v210
	v_pk_fma_f32 v[140:141], v[140:141], v[206:207], v[44:45] op_sel_hi:[1,0,1]
	v_pk_fma_f32 v[142:143], v[142:143], v[206:207], v[46:47] op_sel_hi:[1,0,1]
	v_pk_fma_f32 v[136:137], v[136:137], v[206:207], v[40:41] op_sel_hi:[1,0,1]
	v_pk_fma_f32 v[138:139], v[138:139], v[206:207], v[42:43] op_sel_hi:[1,0,1]
	v_pk_fma_f32 v[132:133], v[132:133], v[206:207], v[36:37] op_sel_hi:[1,0,1]
	v_pk_fma_f32 v[134:135], v[134:135], v[206:207], v[38:39] op_sel_hi:[1,0,1]
	v_pk_fma_f32 v[124:125], v[124:125], v[206:207], v[32:33] op_sel_hi:[1,0,1]
	v_pk_fma_f32 v[126:127], v[126:127], v[206:207], v[34:35] op_sel_hi:[1,0,1]
	v_cvt_pk_bf16_f32 v214, v140, v141
	v_cvt_pk_bf16_f32 v215, v142, v143
	v_cvt_pk_bf16_f32 v216, v136, v137
	v_cvt_pk_bf16_f32 v217, v138, v139
	global_store_dwordx4 v204, v[214:217], s[0:1]
	v_cvt_pk_bf16_f32 v218, v132, v133
	v_cvt_pk_bf16_f32 v219, v134, v135
	v_cvt_pk_bf16_f32 v220, v124, v125
	v_cvt_pk_bf16_f32 v221, v126, v127
	global_store_dwordx4 v204, v[218:221], s[0:1] offset:256
	s_add_u32 s0, s0, 0x8000
	s_addc_u32 s1, s1, 0
	v_fmamk_f32 v212, v238, 0x3a800000, v228
	v_rsq_f32_e32 v212, v212
	v_pk_fma_f32 v[108:109], v[108:109], v[208:209], v[44:45] op_sel_hi:[1,0,1]
	v_pk_fma_f32 v[110:111], v[110:111], v[208:209], v[46:47] op_sel_hi:[1,0,1]
	v_pk_fma_f32 v[100:101], v[100:101], v[208:209], v[40:41] op_sel_hi:[1,0,1]
	v_pk_fma_f32 v[102:103], v[102:103], v[208:209], v[42:43] op_sel_hi:[1,0,1]
	v_pk_fma_f32 v[92:93], v[92:93], v[208:209], v[36:37] op_sel_hi:[1,0,1]
	v_pk_fma_f32 v[94:95], v[94:95], v[208:209], v[38:39] op_sel_hi:[1,0,1]
	v_pk_fma_f32 v[84:85], v[84:85], v[208:209], v[32:33] op_sel_hi:[1,0,1]
	v_pk_fma_f32 v[86:87], v[86:87], v[208:209], v[34:35] op_sel_hi:[1,0,1]
	v_cvt_pk_bf16_f32 v214, v108, v109
	v_cvt_pk_bf16_f32 v215, v110, v111
	v_cvt_pk_bf16_f32 v216, v100, v101
	v_cvt_pk_bf16_f32 v217, v102, v103
	global_store_dwordx4 v204, v[214:217], s[0:1]
	v_cvt_pk_bf16_f32 v218, v92, v93
	v_cvt_pk_bf16_f32 v219, v94, v95
	v_cvt_pk_bf16_f32 v220, v84, v85
	v_cvt_pk_bf16_f32 v221, v86, v87
	global_store_dwordx4 v204, v[218:221], s[0:1] offset:256
	s_add_u32 s0, s0, 0x8000
	s_addc_u32 s1, s1, 0
	v_fmamk_f32 v206, v237, 0x3a800000, v228
	v_rsq_f32_e32 v206, v206
	v_pk_fma_f32 v[172:173], v[172:173], v[210:211], v[44:45] op_sel_hi:[1,0,1]
	v_pk_fma_f32 v[174:175], v[174:175], v[210:211], v[46:47] op_sel_hi:[1,0,1]
	v_pk_fma_f32 v[168:169], v[168:169], v[210:211], v[40:41] op_sel_hi:[1,0,1]
	v_pk_fma_f32 v[170:171], v[170:171], v[210:211], v[42:43] op_sel_hi:[1,0,1]
	v_pk_fma_f32 v[164:165], v[164:165], v[210:211], v[36:37] op_sel_hi:[1,0,1]
	v_pk_fma_f32 v[166:167], v[166:167], v[210:211], v[38:39] op_sel_hi:[1,0,1]
	v_pk_fma_f32 v[160:161], v[160:161], v[210:211], v[32:33] op_sel_hi:[1,0,1]
	v_pk_fma_f32 v[162:163], v[162:163], v[210:211], v[34:35] op_sel_hi:[1,0,1]
	v_cvt_pk_bf16_f32 v214, v172, v173
	v_cvt_pk_bf16_f32 v215, v174, v175
	v_cvt_pk_bf16_f32 v216, v168, v169
	v_cvt_pk_bf16_f32 v217, v170, v171
	global_store_dwordx4 v204, v[214:217], s[0:1]
	v_cvt_pk_bf16_f32 v218, v164, v165
	v_cvt_pk_bf16_f32 v219, v166, v167
	v_cvt_pk_bf16_f32 v220, v160, v161
	v_cvt_pk_bf16_f32 v221, v162, v163
	global_store_dwordx4 v204, v[218:221], s[0:1] offset:256
	s_add_u32 s0, s0, 0x8000
	s_addc_u32 s1, s1, 0
	v_fmamk_f32 v208, v236, 0x3a800000, v228
	v_rsq_f32_e32 v208, v208
	v_pk_fma_f32 v[156:157], v[156:157], v[212:213], v[44:45] op_sel_hi:[1,0,1]
	v_pk_fma_f32 v[158:159], v[158:159], v[212:213], v[46:47] op_sel_hi:[1,0,1]
	v_pk_fma_f32 v[152:153], v[152:153], v[212:213], v[40:41] op_sel_hi:[1,0,1]
	v_pk_fma_f32 v[154:155], v[154:155], v[212:213], v[42:43] op_sel_hi:[1,0,1]
	v_pk_fma_f32 v[148:149], v[148:149], v[212:213], v[36:37] op_sel_hi:[1,0,1]
	v_pk_fma_f32 v[150:151], v[150:151], v[212:213], v[38:39] op_sel_hi:[1,0,1]
	v_pk_fma_f32 v[144:145], v[144:145], v[212:213], v[32:33] op_sel_hi:[1,0,1]
	v_pk_fma_f32 v[146:147], v[146:147], v[212:213], v[34:35] op_sel_hi:[1,0,1]
	v_cvt_pk_bf16_f32 v214, v156, v157
	v_cvt_pk_bf16_f32 v215, v158, v159
	v_cvt_pk_bf16_f32 v216, v152, v153
	v_cvt_pk_bf16_f32 v217, v154, v155
	global_store_dwordx4 v204, v[214:217], s[0:1]
	v_cvt_pk_bf16_f32 v218, v148, v149
	v_cvt_pk_bf16_f32 v219, v150, v151
	v_cvt_pk_bf16_f32 v220, v144, v145
	v_cvt_pk_bf16_f32 v221, v146, v147
	global_store_dwordx4 v204, v[218:221], s[0:1] offset:256
	s_add_u32 s0, s0, 0x28000
	s_addc_u32 s1, s1, 0
	v_fmamk_f32 v210, v234, 0x3a800000, v228
	v_rsq_f32_e32 v210, v210
	v_pk_fma_f32 v[104:105], v[104:105], v[206:207], v[44:45] op_sel_hi:[1,0,1]
	v_pk_fma_f32 v[106:107], v[106:107], v[206:207], v[46:47] op_sel_hi:[1,0,1]
	v_pk_fma_f32 v[96:97], v[96:97], v[206:207], v[40:41] op_sel_hi:[1,0,1]
	v_pk_fma_f32 v[98:99], v[98:99], v[206:207], v[42:43] op_sel_hi:[1,0,1]
	v_pk_fma_f32 v[76:77], v[76:77], v[206:207], v[36:37] op_sel_hi:[1,0,1]
	v_pk_fma_f32 v[78:79], v[78:79], v[206:207], v[38:39] op_sel_hi:[1,0,1]
	v_pk_fma_f32 v[68:69], v[68:69], v[206:207], v[32:33] op_sel_hi:[1,0,1]
	v_pk_fma_f32 v[70:71], v[70:71], v[206:207], v[34:35] op_sel_hi:[1,0,1]
	v_cvt_pk_bf16_f32 v214, v104, v105
	v_cvt_pk_bf16_f32 v215, v106, v107
	v_cvt_pk_bf16_f32 v216, v96, v97
	v_cvt_pk_bf16_f32 v217, v98, v99
	global_store_dwordx4 v204, v[214:217], s[0:1]
	v_cvt_pk_bf16_f32 v218, v76, v77
	v_cvt_pk_bf16_f32 v219, v78, v79
	v_cvt_pk_bf16_f32 v220, v68, v69
	v_cvt_pk_bf16_f32 v221, v70, v71
	global_store_dwordx4 v204, v[218:221], s[0:1] offset:256
	s_add_u32 s0, s0, 0x8000
	s_addc_u32 s1, s1, 0
	v_fmamk_f32 v212, v233, 0x3a800000, v228
	v_rsq_f32_e32 v212, v212
	v_pk_fma_f32 v[60:61], v[60:61], v[208:209], v[44:45] op_sel_hi:[1,0,1]
	v_pk_fma_f32 v[62:63], v[62:63], v[208:209], v[46:47] op_sel_hi:[1,0,1]
	v_pk_fma_f32 v[56:57], v[56:57], v[208:209], v[40:41] op_sel_hi:[1,0,1]
	v_pk_fma_f32 v[58:59], v[58:59], v[208:209], v[42:43] op_sel_hi:[1,0,1]
	v_pk_fma_f32 v[52:53], v[52:53], v[208:209], v[36:37] op_sel_hi:[1,0,1]
	v_pk_fma_f32 v[54:55], v[54:55], v[208:209], v[38:39] op_sel_hi:[1,0,1]
	v_pk_fma_f32 v[48:49], v[48:49], v[208:209], v[32:33] op_sel_hi:[1,0,1]
	v_pk_fma_f32 v[50:51], v[50:51], v[208:209], v[34:35] op_sel_hi:[1,0,1]
	v_cvt_pk_bf16_f32 v214, v60, v61
	v_cvt_pk_bf16_f32 v215, v62, v63
	v_cvt_pk_bf16_f32 v216, v56, v57
	v_cvt_pk_bf16_f32 v217, v58, v59
	global_store_dwordx4 v204, v[214:217], s[0:1]
	v_cvt_pk_bf16_f32 v218, v52, v53
	v_cvt_pk_bf16_f32 v219, v54, v55
	v_cvt_pk_bf16_f32 v220, v48, v49
	v_cvt_pk_bf16_f32 v221, v50, v51
	global_store_dwordx4 v204, v[218:221], s[0:1] offset:256
	s_add_u32 s0, s0, 0x8000
	s_addc_u32 s1, s1, 0
	v_pk_fma_f32 v[28:29], v[28:29], v[210:211], v[44:45] op_sel_hi:[1,0,1]
	v_pk_fma_f32 v[30:31], v[30:31], v[210:211], v[46:47] op_sel_hi:[1,0,1]
	v_pk_fma_f32 v[24:25], v[24:25], v[210:211], v[40:41] op_sel_hi:[1,0,1]
	v_pk_fma_f32 v[26:27], v[26:27], v[210:211], v[42:43] op_sel_hi:[1,0,1]
	v_pk_fma_f32 v[20:21], v[20:21], v[210:211], v[36:37] op_sel_hi:[1,0,1]
	v_pk_fma_f32 v[22:23], v[22:23], v[210:211], v[38:39] op_sel_hi:[1,0,1]
	v_pk_fma_f32 v[16:17], v[16:17], v[210:211], v[32:33] op_sel_hi:[1,0,1]
	v_pk_fma_f32 v[18:19], v[18:19], v[210:211], v[34:35] op_sel_hi:[1,0,1]
	v_cvt_pk_bf16_f32 v214, v28, v29
	v_cvt_pk_bf16_f32 v215, v30, v31
	v_cvt_pk_bf16_f32 v216, v24, v25
	v_cvt_pk_bf16_f32 v217, v26, v27
	global_store_dwordx4 v204, v[214:217], s[0:1]
	v_cvt_pk_bf16_f32 v218, v20, v21
	v_cvt_pk_bf16_f32 v219, v22, v23
	v_cvt_pk_bf16_f32 v220, v16, v17
	v_cvt_pk_bf16_f32 v221, v18, v19
	global_store_dwordx4 v204, v[218:221], s[0:1] offset:256
	s_add_u32 s0, s0, 0x8000
	s_addc_u32 s1, s1, 0
	v_pk_fma_f32 v[12:13], v[12:13], v[212:213], v[44:45] op_sel_hi:[1,0,1]
	v_pk_fma_f32 v[14:15], v[14:15], v[212:213], v[46:47] op_sel_hi:[1,0,1]
	v_pk_fma_f32 v[8:9], v[8:9], v[212:213], v[40:41] op_sel_hi:[1,0,1]
	v_pk_fma_f32 v[10:11], v[10:11], v[212:213], v[42:43] op_sel_hi:[1,0,1]
	v_pk_fma_f32 v[4:5], v[4:5], v[212:213], v[36:37] op_sel_hi:[1,0,1]
	v_pk_fma_f32 v[6:7], v[6:7], v[212:213], v[38:39] op_sel_hi:[1,0,1]
	v_pk_fma_f32 v[0:1], v[0:1], v[212:213], v[32:33] op_sel_hi:[1,0,1]
	v_pk_fma_f32 v[2:3], v[2:3], v[212:213], v[34:35] op_sel_hi:[1,0,1]
	v_cvt_pk_bf16_f32 v214, v12, v13
	v_cvt_pk_bf16_f32 v215, v14, v15
	v_cvt_pk_bf16_f32 v216, v8, v9
	v_cvt_pk_bf16_f32 v217, v10, v11
	global_store_dwordx4 v204, v[214:217], s[0:1]
	v_cvt_pk_bf16_f32 v218, v4, v5
	v_cvt_pk_bf16_f32 v219, v6, v7
	v_cvt_pk_bf16_f32 v220, v0, v1
	v_cvt_pk_bf16_f32 v221, v2, v3
	global_store_dwordx4 v204, v[218:221], s[0:1] offset:256
	s_andn2_b64 vcc, exec, s[6:7]
	s_mov_b64 s[0:1], -1
	s_cbranch_vccnz .LBB0_780
	s_andn2_b64 vcc, exec, s[40:41]
	s_cbranch_vccnz .LBB0_779
	s_barrier
	s_branch .LBB0_779
.Lipfb_slow:
	v_fmamk_f32 v184, v200, 0x3a800000, v228
	v_rsq_f32_e32 v184, v184
	s_cmp_eq_u32 s18, 4
	s_cselect_b64 s[0:1], -1, 0
	s_cmp_eq_u32 s18, 1
	s_cselect_b64 s[8:9], -1, 0
	v_pk_fma_f32 v[142:143], v[142:143], v[184:185], v[46:47] op_sel_hi:[1,0,1]
	v_pk_fma_f32 v[140:141], v[140:141], v[184:185], v[44:45] op_sel_hi:[1,0,1]
	v_pk_fma_f32 v[138:139], v[138:139], v[184:185], v[42:43] op_sel_hi:[1,0,1]
	v_pk_fma_f32 v[136:137], v[136:137], v[184:185], v[40:41] op_sel_hi:[1,0,1]
	v_pk_fma_f32 v[134:135], v[134:135], v[184:185], v[38:39] op_sel_hi:[1,0,1]
	v_pk_fma_f32 v[132:133], v[132:133], v[184:185], v[36:37] op_sel_hi:[1,0,1]
	v_pk_fma_f32 v[126:127], v[126:127], v[184:185], v[34:35] op_sel_hi:[1,0,1]
	v_pk_fma_f32 v[124:125], v[124:125], v[184:185], v[32:33] op_sel_hi:[1,0,1]
	v_cndmask_b32_e64 v184, 0, 1, s[8:9]
	s_mov_b64 s[84:85], -1
	s_and_b64 vcc, exec, s[12:13]
	v_cmp_ne_u32_e64 s[8:9], 1, v184
	s_cbranch_vccz .LBB0_832
	s_and_b64 vcc, exec, s[8:9]
	v_mov_b32_e32 v209, v143
	v_mov_b32_e32 v208, v142
	v_mov_b32_e32 v207, v141
	v_mov_b32_e32 v206, v140
	v_mov_b32_e32 v213, v139
	v_mov_b32_e32 v212, v138
	v_mov_b32_e32 v211, v137
	v_mov_b32_e32 v210, v136
	v_mov_b32_e32 v217, v135
	v_mov_b32_e32 v216, v134
	v_mov_b32_e32 v215, v133
	v_mov_b32_e32 v214, v132
	v_mov_b32_e32 v221, v127
	v_mov_b32_e32 v220, v126
	v_mov_b32_e32 v219, v125
	v_mov_b32_e32 v218, v124
	s_cbranch_vccnz .LBB0_831
	v_and_b32_e32 v201, 0x7fffffff, v141
	v_and_b32_e32 v200, 0x7fffffff, v140
	v_pk_fma_f32 v[200:201], v[200:201], s[54:55], 1.0 op_sel_hi:[1,0,0]
	v_mov_b64_e32 v[220:221], s[62:63]
	v_rcp_f32_e32 v200, v200
	v_rcp_f32_e32 v201, v201
	v_pk_mul_f32 v[208:209], v[140:141], v[140:141]
	v_cmp_gt_f32_e32 vcc, 0, v140
	v_pk_mul_f32 v[208:209], v[208:209], s[72:73] op_sel_hi:[1,0]
	v_pk_fma_f32 v[206:207], v[200:201], s[58:59], v[220:221] op_sel_hi:[1,0,0]
	v_exp_f32_e32 v208, v208
	v_pk_fma_f32 v[206:207], v[200:201], v[206:207], s[64:65] op_sel_hi:[1,1,0]
	v_exp_f32_e32 v209, v209
	v_pk_fma_f32 v[206:207], v[200:201], v[206:207], s[68:69] op_sel_hi:[1,1,0]
	v_pk_mul_f32 v[210:211], v[142:143], v[142:143]
	v_pk_fma_f32 v[206:207], v[200:201], v[206:207], s[70:71] op_sel_hi:[1,1,0]
	v_pk_mul_f32 v[210:211], v[210:211], s[72:73] op_sel_hi:[1,0]
	v_pk_mul_f32 v[200:201], v[200:201], v[206:207]
	v_exp_f32_e32 v210, v210
	v_pk_mul_f32 v[200:201], v[208:209], v[200:201]
	v_and_b32_e32 v209, 0x7fffffff, v143
	v_and_b32_e32 v208, 0x7fffffff, v142
	v_pk_fma_f32 v[208:209], v[208:209], s[54:55], 1.0 op_sel_hi:[1,0,0]
	v_pk_mul_f32 v[206:207], v[140:141], v[200:201]
	v_rcp_f32_e32 v208, v208
	v_rcp_f32_e32 v209, v209
	v_pk_fma_f32 v[200:201], v[140:141], v[200:201], v[140:141] neg_lo:[1,0,0] neg_hi:[1,0,0]
	v_exp_f32_e32 v211, v211
	v_cndmask_b32_e32 v206, v200, v206, vcc
	v_cmp_gt_f32_e32 vcc, 0, v141
	v_pk_mul_f32 v[212:213], v[136:137], v[136:137]
	v_pk_mul_f32 v[214:215], v[138:139], v[138:139]
	v_cndmask_b32_e32 v207, v201, v207, vcc
	v_pk_fma_f32 v[200:201], v[208:209], s[58:59], v[220:221] op_sel_hi:[1,0,0]
	v_cmp_gt_f32_e32 vcc, 0, v142
	v_pk_fma_f32 v[200:201], v[208:209], v[200:201], s[64:65] op_sel_hi:[1,1,0]
	v_pk_mul_f32 v[212:213], v[212:213], s[72:73] op_sel_hi:[1,0]
	v_pk_fma_f32 v[200:201], v[208:209], v[200:201], s[68:69] op_sel_hi:[1,1,0]
	v_exp_f32_e32 v212, v212
	v_pk_fma_f32 v[200:201], v[208:209], v[200:201], s[70:71] op_sel_hi:[1,1,0]
	v_exp_f32_e32 v213, v213
	v_pk_mul_f32 v[200:201], v[208:209], v[200:201]
	v_pk_mul_f32 v[214:215], v[214:215], s[72:73] op_sel_hi:[1,0]
	v_pk_mul_f32 v[200:201], v[210:211], v[200:201]
	v_and_b32_e32 v211, 0x7fffffff, v137
	v_and_b32_e32 v210, 0x7fffffff, v136
	v_pk_fma_f32 v[210:211], v[210:211], s[54:55], 1.0 op_sel_hi:[1,0,0]
	v_pk_mul_f32 v[208:209], v[142:143], v[200:201]
	v_rcp_f32_e32 v210, v210
	v_rcp_f32_e32 v211, v211
	v_pk_fma_f32 v[200:201], v[142:143], v[200:201], v[142:143] neg_lo:[1,0,0] neg_hi:[1,0,0]
	v_exp_f32_e32 v214, v214
	v_cndmask_b32_e32 v208, v200, v208, vcc
	v_cmp_gt_f32_e32 vcc, 0, v143
	v_exp_f32_e32 v215, v215
	v_pk_mul_f32 v[216:217], v[132:133], v[132:133]
	v_cndmask_b32_e32 v209, v201, v209, vcc
	v_pk_fma_f32 v[200:201], v[210:211], s[58:59], v[220:221] op_sel_hi:[1,0,0]
	v_cmp_gt_f32_e32 vcc, 0, v136
	v_pk_fma_f32 v[200:201], v[210:211], v[200:201], s[64:65] op_sel_hi:[1,1,0]
	v_pk_mul_f32 v[216:217], v[216:217], s[72:73] op_sel_hi:[1,0]
	v_pk_fma_f32 v[200:201], v[210:211], v[200:201], s[68:69] op_sel_hi:[1,1,0]
	v_exp_f32_e32 v216, v216
	v_pk_fma_f32 v[200:201], v[210:211], v[200:201], s[70:71] op_sel_hi:[1,1,0]
	v_exp_f32_e32 v217, v217
	v_pk_mul_f32 v[200:201], v[210:211], v[200:201]
	v_pk_mul_f32 v[218:219], v[134:135], v[134:135]
	v_pk_mul_f32 v[200:201], v[212:213], v[200:201]
	v_and_b32_e32 v213, 0x7fffffff, v139
	v_and_b32_e32 v212, 0x7fffffff, v138
	v_pk_fma_f32 v[212:213], v[212:213], s[54:55], 1.0 op_sel_hi:[1,0,0]
	v_pk_mul_f32 v[210:211], v[136:137], v[200:201]
	v_rcp_f32_e32 v212, v212
	v_rcp_f32_e32 v213, v213
	v_pk_fma_f32 v[200:201], v[136:137], v[200:201], v[136:137] neg_lo:[1,0,0] neg_hi:[1,0,0]
	v_pk_mul_f32 v[218:219], v[218:219], s[72:73] op_sel_hi:[1,0]
	v_cndmask_b32_e32 v210, v200, v210, vcc
	v_cmp_gt_f32_e32 vcc, 0, v137
	v_exp_f32_e32 v218, v218
	v_exp_f32_e32 v219, v219
	v_cndmask_b32_e32 v211, v201, v211, vcc
	v_pk_fma_f32 v[200:201], v[212:213], s[58:59], v[220:221] op_sel_hi:[1,0,0]
	v_cmp_gt_f32_e32 vcc, 0, v138
	v_pk_fma_f32 v[200:201], v[212:213], v[200:201], s[64:65] op_sel_hi:[1,1,0]
	v_pk_mul_f32 v[240:241], v[124:125], v[124:125]
	v_pk_fma_f32 v[200:201], v[212:213], v[200:201], s[68:69] op_sel_hi:[1,1,0]
	v_pk_mul_f32 v[240:241], v[240:241], s[72:73] op_sel_hi:[1,0]
	v_pk_fma_f32 v[200:201], v[212:213], v[200:201], s[70:71] op_sel_hi:[1,1,0]
	v_exp_f32_e32 v240, v240
	v_pk_mul_f32 v[200:201], v[212:213], v[200:201]
	v_exp_f32_e32 v241, v241
	v_pk_mul_f32 v[200:201], v[214:215], v[200:201]
	v_and_b32_e32 v215, 0x7fffffff, v133
	v_and_b32_e32 v214, 0x7fffffff, v132
	v_pk_fma_f32 v[214:215], v[214:215], s[54:55], 1.0 op_sel_hi:[1,0,0]
	v_pk_mul_f32 v[212:213], v[138:139], v[200:201]
	v_rcp_f32_e32 v214, v214
	v_rcp_f32_e32 v215, v215
	v_pk_fma_f32 v[200:201], v[138:139], v[200:201], v[138:139] neg_lo:[1,0,0] neg_hi:[1,0,0]
	v_pk_mul_f32 v[242:243], v[126:127], v[126:127]
	v_cndmask_b32_e32 v212, v200, v212, vcc
	v_cmp_gt_f32_e32 vcc, 0, v139
	v_add_f32_e32 v184, 0, v206
	v_add_f32_e32 v184, v207, v184
	v_cndmask_b32_e32 v213, v201, v213, vcc
	v_pk_fma_f32 v[200:201], v[214:215], s[58:59], v[220:221] op_sel_hi:[1,0,0]
	v_cmp_gt_f32_e32 vcc, 0, v132
	v_pk_fma_f32 v[200:201], v[214:215], v[200:201], s[64:65] op_sel_hi:[1,1,0]
	v_add_f32_e32 v184, v208, v184
	v_pk_fma_f32 v[200:201], v[214:215], v[200:201], s[68:69] op_sel_hi:[1,1,0]
	v_add_f32_e32 v184, v209, v184
	v_pk_fma_f32 v[200:201], v[214:215], v[200:201], s[70:71] op_sel_hi:[1,1,0]
	v_add_f32_e32 v184, v210, v184
	v_pk_mul_f32 v[200:201], v[214:215], v[200:201]
	v_add_f32_e32 v184, v211, v184
	v_pk_mul_f32 v[200:201], v[216:217], v[200:201]
	v_and_b32_e32 v217, 0x7fffffff, v135
	v_and_b32_e32 v216, 0x7fffffff, v134
	v_pk_fma_f32 v[216:217], v[216:217], s[54:55], 1.0 op_sel_hi:[1,0,0]
	v_pk_mul_f32 v[214:215], v[132:133], v[200:201]
	v_rcp_f32_e32 v216, v216
	v_rcp_f32_e32 v217, v217
	v_pk_fma_f32 v[200:201], v[132:133], v[200:201], v[132:133] neg_lo:[1,0,0] neg_hi:[1,0,0]
	v_add_f32_e32 v184, v212, v184
	v_cndmask_b32_e32 v214, v200, v214, vcc
	v_cmp_gt_f32_e32 vcc, 0, v133
	v_add_f32_e32 v184, v213, v184
	v_add_f32_e32 v184, v214, v184
	v_cndmask_b32_e32 v215, v201, v215, vcc
	v_pk_fma_f32 v[200:201], v[216:217], s[58:59], v[220:221] op_sel_hi:[1,0,0]
	v_cmp_gt_f32_e32 vcc, 0, v134
	v_pk_fma_f32 v[200:201], v[216:217], v[200:201], s[64:65] op_sel_hi:[1,1,0]
	v_add_f32_e32 v184, v215, v184
	v_pk_fma_f32 v[200:201], v[216:217], v[200:201], s[68:69] op_sel_hi:[1,1,0]
	v_and_b32_e32 v203, 64, v229
	v_pk_fma_f32 v[200:201], v[216:217], v[200:201], s[70:71] op_sel_hi:[1,1,0]
	v_add_u32_e32 v203, 64, v203
	v_pk_mul_f32 v[200:201], v[216:217], v[200:201]
	s_nop 0
	v_pk_mul_f32 v[200:201], v[218:219], v[200:201]
	v_and_b32_e32 v219, 0x7fffffff, v125
	v_and_b32_e32 v218, 0x7fffffff, v124
	v_pk_fma_f32 v[218:219], v[218:219], s[54:55], 1.0 op_sel_hi:[1,0,0]
	v_pk_mul_f32 v[216:217], v[134:135], v[200:201]
	v_rcp_f32_e32 v218, v218
	v_rcp_f32_e32 v219, v219
	v_pk_fma_f32 v[200:201], v[134:135], v[200:201], v[134:135] neg_lo:[1,0,0] neg_hi:[1,0,0]
	s_nop 0
	v_cndmask_b32_e32 v216, v200, v216, vcc
	v_cmp_gt_f32_e32 vcc, 0, v135
	v_add_f32_e32 v184, v216, v184
	s_nop 0
	v_cndmask_b32_e32 v217, v201, v217, vcc
	v_pk_fma_f32 v[200:201], v[218:219], s[58:59], v[220:221] op_sel_hi:[1,0,0]
	v_cmp_gt_f32_e32 vcc, 0, v124
	v_pk_fma_f32 v[200:201], v[218:219], v[200:201], s[64:65] op_sel_hi:[1,1,0]
	v_add_f32_e32 v184, v217, v184
	v_pk_fma_f32 v[200:201], v[218:219], v[200:201], s[68:69] op_sel_hi:[1,1,0]
	s_nop 0
	v_pk_fma_f32 v[200:201], v[218:219], v[200:201], s[70:71] op_sel_hi:[1,1,0]
	s_nop 0
	v_pk_mul_f32 v[200:201], v[218:219], v[200:201]
	s_nop 0
	v_pk_mul_f32 v[200:201], v[240:241], v[200:201]
	v_and_b32_e32 v241, 0x7fffffff, v127
	v_and_b32_e32 v240, 0x7fffffff, v126
	v_pk_fma_f32 v[240:241], v[240:241], s[54:55], 1.0 op_sel_hi:[1,0,0]
	v_pk_mul_f32 v[218:219], v[124:125], v[200:201]
	v_rcp_f32_e32 v240, v240
	v_rcp_f32_e32 v241, v241
	v_pk_fma_f32 v[200:201], v[124:125], v[200:201], v[124:125] neg_lo:[1,0,0] neg_hi:[1,0,0]
	s_nop 0
	v_cndmask_b32_e32 v218, v200, v218, vcc
	v_cmp_gt_f32_e32 vcc, 0, v125
	v_add_f32_e32 v184, v218, v184
	s_nop 0
	v_cndmask_b32_e32 v219, v201, v219, vcc
	v_pk_fma_f32 v[200:201], v[240:241], s[58:59], v[220:221] op_sel_hi:[1,0,0]
	v_pk_mul_f32 v[220:221], v[242:243], s[72:73] op_sel_hi:[1,0]
	v_pk_fma_f32 v[200:201], v[240:241], v[200:201], s[64:65] op_sel_hi:[1,1,0]
	v_exp_f32_e32 v220, v220
	v_exp_f32_e32 v221, v221
	v_pk_fma_f32 v[200:201], v[240:241], v[200:201], s[68:69] op_sel_hi:[1,1,0]
	v_cmp_gt_f32_e32 vcc, 0, v126
	v_pk_fma_f32 v[200:201], v[240:241], v[200:201], s[70:71] op_sel_hi:[1,1,0]
	v_add_f32_e32 v184, v219, v184
	v_pk_mul_f32 v[200:201], v[240:241], v[200:201]
	s_nop 0
	v_pk_mul_f32 v[200:201], v[220:221], v[200:201]
	s_nop 0
	v_pk_mul_f32 v[220:221], v[126:127], v[200:201]
	v_pk_fma_f32 v[200:201], v[126:127], v[200:201], v[126:127] neg_lo:[1,0,0] neg_hi:[1,0,0]
	s_nop 0
	v_cndmask_b32_e32 v220, v200, v220, vcc
	v_cmp_gt_f32_e32 vcc, 0, v127
	v_xor_b32_e32 v200, 16, v229
	v_add_f32_e32 v184, v220, v184
	v_cndmask_b32_e32 v221, v201, v221, vcc
	v_mul_f32_e32 v201, v207, v207
	v_fmac_f32_e32 v201, v206, v206
	v_fmac_f32_e32 v201, v208, v208
	v_fmac_f32_e32 v201, v209, v209
	v_fmac_f32_e32 v201, v210, v210
	v_fmac_f32_e32 v201, v211, v211
	v_fmac_f32_e32 v201, v212, v212
	v_fmac_f32_e32 v201, v213, v213
	v_fmac_f32_e32 v201, v214, v214
	v_fmac_f32_e32 v201, v215, v215
	v_fmac_f32_e32 v201, v216, v216
	v_cmp_lt_i32_e32 vcc, v200, v203
	v_fmac_f32_e32 v201, v217, v217
	v_add_f32_e32 v184, v221, v184
	v_cndmask_b32_e32 v200, v229, v200, vcc
	v_lshlrev_b32_e32 v200, 2, v200
	v_fmac_f32_e32 v201, v218, v218
	ds_bpermute_b32 v205, v200, v184
	v_fmac_f32_e32 v201, v219, v219
	v_fmac_f32_e32 v201, v220, v220
	v_fmac_f32_e32 v201, v221, v221
	ds_bpermute_b32 v240, v200, v201
	s_waitcnt lgkmcnt(1)
	v_add_f32_e32 v184, v184, v205
	v_xor_b32_e32 v205, 32, v229
	v_cmp_lt_i32_e32 vcc, v205, v203
	s_waitcnt lgkmcnt(0)
	v_add_f32_e32 v201, v201, v240
	v_cndmask_b32_e32 v200, v229, v205, vcc
	v_lshlrev_b32_e32 v203, 2, v200
	ds_bpermute_b32 v200, v203, v184
	ds_bpermute_b32 v203, v203, v201
	s_and_saveexec_b64 s[84:85], s[4:5]
	s_cbranch_execz .LBB0_830
	v_lshlrev_b64 v[240:241], 2, v[198:199]
	v_lshl_add_u64 v[242:243], s[14:15], 0, v[240:241]
	v_lshl_add_u64 v[240:241], s[52:53], 0, v[240:241]
	s_waitcnt lgkmcnt(1)
	v_add_f32_e32 v184, v184, v200
	s_waitcnt lgkmcnt(0)
	v_add_f32_e32 v200, v201, v203
	global_atomic_add_f32 v[240:241], v184, off
	global_atomic_add_f32 v[242:243], v200, off
